# weight conversion rewritten without LDS/barriers: each lane owns an 8k x 4n block, 128B-coalesced loads and stores, double-buffered per wave
# speedup vs baseline: 1.0124x; 1.0124x over previous
; __device__ __forceinline__ void transpose_big(const Lt& lt, const float* src, bf16_t* dst, const float* scale, int K, int N, int tlo, int thi, int phase, int c, int nc, float* tile) {
;     ...
;     const int first = tlo + (((c - (tlo + phase)) % nc) + nc) % nc;
;     const int kr = tid >> 5, nc4 = (tid & 31) * 4;
;     const int on = tid & 127, okc = (tid >> 7) * 32;
;     f32x4 pre[8];
;     if (first < thi) { const int k0 = (first / tn) * 128, n0 = (first % tn) * 128;
; #pragma unroll
;         for (int h = 0; h < 8; ++h) pre[h] = __builtin_nontemporal_load((const f32x4*)(src + (size_t)(k0 + kr + 16 * h) * N + n0 + nc4)); }
; __device__ __forceinline__ void convert_layer(const Params& p, const Lt& lt, int l, int glo, int ghi, int c, int nc, float* tile) {
;     unsigned char* ws = p.ws;
; #pragma unroll 1
;     for (int m = 0; m < 4; ++m) {
;         const int off = m == 0 ? 0 : (m == 1 ? 608 : (m == 2 ? 864 : 1888)), n = m == 0 ? 608 : (m == 1 ? 256 : 1024);
;         const int lo = (glo > off ? glo : off) - off, hi = (ghi < off + n ? ghi : off + n) - off;
;         if (lo >= hi) continue;
;         const float* src = m == 0 ? p.in[2] + (size_t)l * DM * INC : (m == 1 ? p.in[21] + (size_t)l * DM * DM : (m == 2 ? p.in[23] + (size_t)l * DM * DFF : p.in[24] + (size_t)l * DFF * DM));
;         bf16_t* dst = (bf16_t*)(m == 0 ? ws + WS_WIN + l * SZ_WIN : (m == 1 ? ws + WS_WOUT + l * SZ_WOUT : (m == 2 ? ws + WS_WUP + l * SZ_WUP : ws + WS_WDN + l * SZ_WDN)));
;         const float* scale = m == 0 ? p.in[1] + l * DM : (m == 2 ? p.in[22] + l * DM : nullptr);
;         const int K = m == 3 ? DFF : DM, N = m == 0 ? INC : (m == 2 ? DFF : DM);
;         transpose_big(lt, src, dst, scale, K, N, lo, hi, off - glo, c, nc, tile);
.LBB0_228:
	v_readlane_b32 s0, v253, 52
	v_readlane_b32 s1, v253, 53
	s_andn2_b64 vcc, exec, s[0:1]
	s_cbranch_vccnz .LBB0_259
	s_cmp_gt_i32 s60, 27
	s_cselect_b64 s[0:1], -1, 0
	s_cmpk_lt_i32 s86, 0x70
	s_cselect_b64 s[4:5], -1, 0
	s_or_b64 s[0:1], s[0:1], s[4:5]
	s_and_b64 vcc, exec, s[0:1]
	s_cbranch_vccnz .LBB0_259
	v_readlane_b32 s37, v254, 1
	s_add_i32 s37, s37, 1
	s_add_i32 s34, s86, 0xffffff90
	s_movk_i32 s35, 0x360
	s_movk_i32 s36, 0x90
	s_mov_b32 s38, 2
	s_branch .Lconv_entry
.Lconv_entry:
	v_and_b32_e32 v4, 63, v245
	v_lshrrev_b32_e32 v5, 6, v245
	s_nop 0
	v_readfirstlane_b32 s0, v5
	v_lshrrev_b32_e32 v6, 3, v4
	v_and_b32_e32 v7, 7, v4
	s_lshr_b32 s1, s0, 2
	s_and_b32 s0, s0, 3
	s_lshl_b32 s1, s1, 6
	s_lshl_b32 s0, s0, 5
	v_lshl_add_u32 v6, v6, 3, s1
	v_lshl_add_u32 v7, v7, 2, s0
	v_lshlrev_b32_e32 v8, 2, v6
	v_lshlrev_b32_e32 v9, 2, v7
	v_lshlrev_b32_e32 v10, 1, v6
	s_cmp_ge_u32 s34, s35
	s_cbranch_scc1 .Lconv_return
	s_mov_b32 s52, s34
	v_readlane_b32 s42, v253, 63
	v_readlane_b32 s43, v254, 0
	s_cmpk_lt_u32 s52, 0x260
	s_cbranch_scc1 .Lconv_i0_m0
	s_cmpk_lt_u32 s52, 0x360
	s_cbranch_scc1 .Lconv_i0_m1
	s_cmpk_lt_u32 s52, 0x760
	s_cbranch_scc1 .Lconv_i0_m2
	s_sub_u32 s0, s52, 0x760
	s_and_b32 s1, s0, 15
	s_lshr_b32 s0, s0, 4
	v_readlane_b32 s40, v253, 23
	v_readlane_b32 s41, v253, 24
	s_mov_b32 s8, s37
	s_mov_b32 s9, 0
	s_lshl_b64 s[4:5], s[8:9], 26
	s_add_u32 s40, s40, s4
	s_addc_u32 s41, s41, s5
	s_lshl_b64 s[4:5], s[8:9], 25
	s_add_u32 s42, s42, s4
	s_addc_u32 s43, s43, s5
	s_add_u32 s42, s42, 0xec00000
	s_addc_u32 s43, s43, 0
	v_readlane_b32 s28, v252, 62
	v_readlane_b32 s29, v252, 63
	s_movk_i32 s30, 0x2000
	s_movk_i32 s46, 0x4000
	s_mov_b32 s47, 0
	s_branch .Lconv_i0_dec
.Lconv_i0_m0:
	s_mul_hi_u32 s0, s52, 0x6bca1b0
	s_mul_i32 s1, s0, 38
	s_sub_u32 s1, s52, s1
	v_readlane_b32 s40, v253, 0
	v_readlane_b32 s41, v253, 1
	s_mul_i32 s4, s37, 0x2600000
	s_mul_hi_u32 s5, s37, 0x2600000
	s_add_u32 s40, s40, s4
	s_addc_u32 s41, s41, s5
	s_mul_i32 s4, s37, 0x1300000
	s_mul_hi_u32 s5, s37, 0x1300000
	s_add_u32 s42, s42, s4
	s_addc_u32 s43, s43, s5
	v_readlane_b32 s28, v252, 62
	v_readlane_b32 s29, v252, 63
	s_lshl_b32 s4, s37, 13
	s_add_u32 s28, s28, s4
	s_addc_u32 s29, s29, 0
	s_movk_i32 s30, 0x4c00
	s_movk_i32 s46, 0x1000
	s_mov_b32 s47, 1
	s_branch .Lconv_i0_dec
.Lconv_i0_m1:
	s_sub_u32 s0, s52, 0x260
	s_and_b32 s1, s0, 15
	s_lshr_b32 s0, s0, 4
	s_mov_b32 s8, s37
	s_mov_b32 s9, 0
	s_lshl_b64 s[4:5], s[8:9], 24
	s_add_u32 s40, s22, s4
	s_addc_u32 s41, s23, s5
	s_lshl_b64 s[4:5], s[8:9], 23
	s_add_u32 s42, s42, s4
	s_addc_u32 s43, s43, s5
	s_add_u32 s42, s42, 0x4c00000
	s_addc_u32 s43, s43, 0
	v_readlane_b32 s28, v252, 62
	v_readlane_b32 s29, v252, 63
	s_movk_i32 s30, 0x2000
	s_movk_i32 s46, 0x1000
	s_mov_b32 s47, 0
	s_branch .Lconv_i0_dec
.Lconv_i0_m2:
	s_sub_u32 s0, s52, 0x360
	s_and_b32 s1, s0, 63
	s_lshr_b32 s0, s0, 6
	s_mov_b32 s8, s37
	s_mov_b32 s9, 0
	s_lshl_b64 s[4:5], s[8:9], 26
	s_add_u32 s40, s26, s4
	s_addc_u32 s41, s27, s5
	s_lshl_b64 s[4:5], s[8:9], 25
	s_add_u32 s42, s42, s4
	s_addc_u32 s43, s43, s5
	s_add_u32 s42, s42, 0x6c00000
	s_addc_u32 s43, s43, 0
	s_lshl_b32 s4, s37, 13
	s_add_u32 s28, s24, s4
	s_addc_u32 s29, s25, 0
	s_mov_b32 s30, 0x8000
	s_movk_i32 s46, 0x1000
	s_mov_b32 s47, 1
.Lconv_i0_dec:
	s_lshl_b32 s4, s30, 7
	s_mul_i32 s4, s4, s0
	s_lshl_b32 s5, s1, 9
	s_add_u32 s4, s4, s5
	s_add_u32 s40, s40, s4
	s_addc_u32 s41, s41, 0
	s_lshl_b32 s4, s46, 7
	s_mul_i32 s4, s4, s1
	s_lshl_b32 s5, s0, 8
	s_add_u32 s4, s4, s5
	s_add_u32 s44, s42, s4
	s_addc_u32 s45, s43, 0
	s_lshl_b32 s4, s0, 9
	s_mul_i32 s4, s4, s47
	s_add_u32 s28, s28, s4
	s_addc_u32 s29, s29, 0
	v_mad_u32_u24 v11, v6, s30, v9
	global_load_dwordx4 v[16:19], v11, s[40:41] nt
	s_add_u32 s40, s40, s30
	s_addc_u32 s41, s41, 0
	global_load_dwordx4 v[20:23], v11, s[40:41] nt
	s_add_u32 s40, s40, s30
	s_addc_u32 s41, s41, 0
	global_load_dwordx4 v[24:27], v11, s[40:41] nt
	s_add_u32 s40, s40, s30
	s_addc_u32 s41, s41, 0
	global_load_dwordx4 v[28:31], v11, s[40:41] nt
	s_add_u32 s40, s40, s30
	s_addc_u32 s41, s41, 0
	global_load_dwordx4 v[32:35], v11, s[40:41] nt
	s_add_u32 s40, s40, s30
	s_addc_u32 s41, s41, 0
	global_load_dwordx4 v[36:39], v11, s[40:41] nt
	s_add_u32 s40, s40, s30
	s_addc_u32 s41, s41, 0
	global_load_dwordx4 v[40:43], v11, s[40:41] nt
	s_add_u32 s40, s40, s30
	s_addc_u32 s41, s41, 0
	global_load_dwordx4 v[44:47], v11, s[40:41] nt
	global_load_dwordx4 v[48:51], v8, s[28:29]
	global_load_dwordx4 v[52:55], v8, s[28:29] offset:16
	s_mov_b32 s39, 1
; __device__ __forceinline__ void lds_barrier() { asm volatile("s_waitcnt lgkmcnt(0)" ::: "memory"); __builtin_amdgcn_s_barrier(); asm volatile("" ::: "memory"); }
; __device__ __forceinline__ void transpose_big(const Lt& lt, const float* src, bf16_t* dst, const float* scale, int K, int N, int tlo, int thi, int phase, int c, int nc, float* tile) {
;     ...
;     for (int t = first; t < thi; t += nc) {
;         const int k0 = (t / tn) * 128, n0 = (t % tn) * 128;
; #pragma unroll
;         for (int h = 0; h < 8; ++h) { float* tp = tile + (kr + 16 * h) * 129 + nc4; tp[0] = pre[h][0]; tp[1] = pre[h][1]; tp[2] = pre[h][2]; tp[3] = pre[h][3]; }
;         lds_barrier();
;         const int tnx = t + nc;
;         if (tnx < thi) { const int k1 = (tnx / tn) * 128, n1 = (tnx % tn) * 128;
; #pragma unroll
;             for (int h = 0; h < 8; ++h) pre[h] = __builtin_nontemporal_load((const f32x4*)(src + (size_t)(k1 + kr + 16 * h) * N + n1 + nc4)); }
; __device__ __forceinline__ void convert_layer(const Params& p, const Lt& lt, int l, int glo, int ghi, int c, int nc, float* tile) {
;     ...
;         const int off = m == 0 ? 0 : (m == 1 ? 608 : (m == 2 ? 864 : 1888)), n = m == 0 ? 608 : (m == 1 ? 256 : 1024);
;         const int lo = (glo > off ? glo : off) - off, hi = (ghi < off + n ? ghi : off + n) - off;
;         if (lo >= hi) continue;
;         const float* src = m == 0 ? p.in[2] + (size_t)l * DM * INC : (m == 1 ? p.in[21] + (size_t)l * DM * DM : (m == 2 ? p.in[23] + (size_t)l * DM * DFF : p.in[24] + (size_t)l * DFF * DM));
;         bf16_t* dst = (bf16_t*)(m == 0 ? ws + WS_WIN + l * SZ_WIN : (m == 1 ? ws + WS_WOUT + l * SZ_WOUT : (m == 2 ? ws + WS_WUP + l * SZ_WUP : ws + WS_WDN + l * SZ_WDN)));
;         const float* scale = m == 0 ? p.in[1] + l * DM : (m == 2 ? p.in[22] + l * DM : nullptr);
;         const int K = m == 3 ? DFF : DM, N = m == 0 ? INC : (m == 2 ? DFF : DM);
.Lconv_loopA:
	s_add_u32 s52, s34, s36
	s_cmp_lt_u32 s52, s35
	s_cselect_b32 s53, 1, 0
	s_cbranch_scc0 .Lconv_A_nonext
	v_readlane_b32 s42, v253, 63
	v_readlane_b32 s43, v254, 0
	s_cmpk_lt_u32 s52, 0x260
	s_cbranch_scc1 .Lconv_iB_m0
	s_cmpk_lt_u32 s52, 0x360
	s_cbranch_scc1 .Lconv_iB_m1
	s_cmpk_lt_u32 s52, 0x760
	s_cbranch_scc1 .Lconv_iB_m2
	s_sub_u32 s0, s52, 0x760
	s_and_b32 s1, s0, 15
	s_lshr_b32 s0, s0, 4
	v_readlane_b32 s40, v253, 23
	v_readlane_b32 s41, v253, 24
	s_mov_b32 s8, s37
	s_mov_b32 s9, 0
	s_lshl_b64 s[4:5], s[8:9], 26
	s_add_u32 s40, s40, s4
	s_addc_u32 s41, s41, s5
	s_lshl_b64 s[4:5], s[8:9], 25
	s_add_u32 s42, s42, s4
	s_addc_u32 s43, s43, s5
	s_add_u32 s42, s42, 0xec00000
	s_addc_u32 s43, s43, 0
	v_readlane_b32 s28, v252, 62
	v_readlane_b32 s29, v252, 63
	s_movk_i32 s30, 0x2000
	s_movk_i32 s50, 0x4000
	s_mov_b32 s51, 0
	s_branch .Lconv_iB_dec
.Lconv_iB_m0:
	s_mul_hi_u32 s0, s52, 0x6bca1b0
	s_mul_i32 s1, s0, 38
	s_sub_u32 s1, s52, s1
	v_readlane_b32 s40, v253, 0
	v_readlane_b32 s41, v253, 1
	s_mul_i32 s4, s37, 0x2600000
	s_mul_hi_u32 s5, s37, 0x2600000
	s_add_u32 s40, s40, s4
	s_addc_u32 s41, s41, s5
	s_mul_i32 s4, s37, 0x1300000
	s_mul_hi_u32 s5, s37, 0x1300000
	s_add_u32 s42, s42, s4
	s_addc_u32 s43, s43, s5
	v_readlane_b32 s28, v252, 62
	v_readlane_b32 s29, v252, 63
	s_lshl_b32 s4, s37, 13
	s_add_u32 s28, s28, s4
	s_addc_u32 s29, s29, 0
	s_movk_i32 s30, 0x4c00
	s_movk_i32 s50, 0x1000
	s_mov_b32 s51, 1
	s_branch .Lconv_iB_dec
.Lconv_iB_m1:
	s_sub_u32 s0, s52, 0x260
	s_and_b32 s1, s0, 15
	s_lshr_b32 s0, s0, 4
	s_mov_b32 s8, s37
	s_mov_b32 s9, 0
	s_lshl_b64 s[4:5], s[8:9], 24
	s_add_u32 s40, s22, s4
	s_addc_u32 s41, s23, s5
	s_lshl_b64 s[4:5], s[8:9], 23
	s_add_u32 s42, s42, s4
	s_addc_u32 s43, s43, s5
	s_add_u32 s42, s42, 0x4c00000
	s_addc_u32 s43, s43, 0
	v_readlane_b32 s28, v252, 62
	v_readlane_b32 s29, v252, 63
	s_movk_i32 s30, 0x2000
	s_movk_i32 s50, 0x1000
	s_mov_b32 s51, 0
	s_branch .Lconv_iB_dec
.Lconv_iB_m2:
	s_sub_u32 s0, s52, 0x360
	s_and_b32 s1, s0, 63
	s_lshr_b32 s0, s0, 6
	s_mov_b32 s8, s37
	s_mov_b32 s9, 0
	s_lshl_b64 s[4:5], s[8:9], 26
	s_add_u32 s40, s26, s4
	s_addc_u32 s41, s27, s5
	s_lshl_b64 s[4:5], s[8:9], 25
	s_add_u32 s42, s42, s4
	s_addc_u32 s43, s43, s5
	s_add_u32 s42, s42, 0x6c00000
	s_addc_u32 s43, s43, 0
	s_lshl_b32 s4, s37, 13
	s_add_u32 s28, s24, s4
	s_addc_u32 s29, s25, 0
	s_mov_b32 s30, 0x8000
	s_movk_i32 s50, 0x1000
	s_mov_b32 s51, 1
.Lconv_iB_dec:
	s_lshl_b32 s4, s30, 7
	s_mul_i32 s4, s4, s0
	s_lshl_b32 s5, s1, 9
	s_add_u32 s4, s4, s5
	s_add_u32 s40, s40, s4
	s_addc_u32 s41, s41, 0
	s_lshl_b32 s4, s50, 7
	s_mul_i32 s4, s4, s1
	s_lshl_b32 s5, s0, 8
	s_add_u32 s4, s4, s5
	s_add_u32 s48, s42, s4
	s_addc_u32 s49, s43, 0
	s_lshl_b32 s4, s0, 9
	s_mul_i32 s4, s4, s51
	s_add_u32 s28, s28, s4
	s_addc_u32 s29, s29, 0
	v_mad_u32_u24 v11, v6, s30, v9
	global_load_dwordx4 v[56:59], v11, s[40:41] nt
	s_add_u32 s40, s40, s30
	s_addc_u32 s41, s41, 0
	global_load_dwordx4 v[60:63], v11, s[40:41] nt
	s_add_u32 s40, s40, s30
	s_addc_u32 s41, s41, 0
	global_load_dwordx4 v[64:67], v11, s[40:41] nt
	s_add_u32 s40, s40, s30
	s_addc_u32 s41, s41, 0
	global_load_dwordx4 v[68:71], v11, s[40:41] nt
	s_add_u32 s40, s40, s30
	s_addc_u32 s41, s41, 0
	global_load_dwordx4 v[72:75], v11, s[40:41] nt
	s_add_u32 s40, s40, s30
	s_addc_u32 s41, s41, 0
	global_load_dwordx4 v[76:79], v11, s[40:41] nt
	s_add_u32 s40, s40, s30
	s_addc_u32 s41, s41, 0
	global_load_dwordx4 v[80:83], v11, s[40:41] nt
	s_add_u32 s40, s40, s30
	s_addc_u32 s41, s41, 0
	global_load_dwordx4 v[84:87], v11, s[40:41] nt
	global_load_dwordx4 v[88:91], v8, s[28:29]
	global_load_dwordx4 v[92:95], v8, s[28:29] offset:16
	s_cmp_eq_u32 s39, 1
	s_cbranch_scc1 .Lconv_A_w10
	s_waitcnt vmcnt(14)
	s_branch .Lconv_A_go
.Lconv_A_w10:
	s_waitcnt vmcnt(10)
	s_branch .Lconv_A_go
.Lconv_A_nonext:
	s_cmp_eq_u32 s39, 1
	s_cbranch_scc1 .Lconv_A_w0
	s_waitcnt vmcnt(4)
	s_branch .Lconv_A_go

; __device__ __forceinline__ unsigned cvt_pk_bf16(float lo, float hi) { const f32x2 v = {lo, hi}; return __builtin_bit_cast(unsigned, __builtin_convertvector(v, bf16x2_t)); }
; __device__ __forceinline__ void transpose_big(const Lt& lt, const float* src, bf16_t* dst, const float* scale, int K, int N, int tlo, int thi, int phase, int c, int nc, float* tile) {
;     ...
;         bf16_t* dp = dst + (size_t)(n0 + on) * K + k0 + okc;
; #pragma unroll
;         for (int q = 0; q < 4; ++q) {
;             float v[8];
; #pragma unroll
;             for (int i = 0; i < 8; ++i) v[i] = tile[(okc + q * 8 + i) * 129 + on];
;             if (scale) {
;                 const f32x4 s0 = *(const f32x4*)(scale + k0 + okc + q * 8), s1 = *(const f32x4*)(scale + k0 + okc + q * 8 + 4);
; #pragma unroll
;                 for (int i = 0; i < 4; ++i) { v[i] *= s0[i]; v[4 + i] *= s1[i]; }
;             }
;             u32x4 w; w.x = cvt_pk_bf16(v[0], v[1]); w.y = cvt_pk_bf16(v[2], v[3]); w.z = cvt_pk_bf16(v[4], v[5]); w.w = cvt_pk_bf16(v[6], v[7]);
;             *(u32x4*)(dp + q * 8) = w;
;         }
.Lconv_A_go:
	s_cmp_eq_u32 s47, 1
	s_cbranch_scc1 .Lconv_cA_hs
	v_mov_b32_e32 v48, 1.0
	v_mov_b32_e32 v49, 1.0
	v_mov_b32_e32 v50, 1.0
	v_mov_b32_e32 v51, 1.0
	v_mov_b32_e32 v52, 1.0
	v_mov_b32_e32 v53, 1.0
	v_mov_b32_e32 v54, 1.0
	v_mov_b32_e32 v55, 1.0
.Lconv_cA_hs:
	v_mul_f32_e32 v16, v16, v48
	v_mul_f32_e32 v17, v17, v48
	v_mul_f32_e32 v18, v18, v48
	v_mul_f32_e32 v19, v19, v48
	v_mul_f32_e32 v20, v20, v49
	v_mul_f32_e32 v21, v21, v49
	v_mul_f32_e32 v22, v22, v49
	v_mul_f32_e32 v23, v23, v49
	v_mul_f32_e32 v24, v24, v50
	v_mul_f32_e32 v25, v25, v50
	v_mul_f32_e32 v26, v26, v50
	v_mul_f32_e32 v27, v27, v50
	v_mul_f32_e32 v28, v28, v51
	v_mul_f32_e32 v29, v29, v51
	v_mul_f32_e32 v30, v30, v51
	v_mul_f32_e32 v31, v31, v51
	v_mul_f32_e32 v32, v32, v52
	v_mul_f32_e32 v33, v33, v52
	v_mul_f32_e32 v34, v34, v52
	v_mul_f32_e32 v35, v35, v52
	v_mul_f32_e32 v36, v36, v53
	v_mul_f32_e32 v37, v37, v53
	v_mul_f32_e32 v38, v38, v53
	v_mul_f32_e32 v39, v39, v53
	v_mul_f32_e32 v40, v40, v54
	v_mul_f32_e32 v41, v41, v54
	v_mul_f32_e32 v42, v42, v54
	v_mul_f32_e32 v43, v43, v54
	v_mul_f32_e32 v44, v44, v55
	v_mul_f32_e32 v45, v45, v55
	v_mul_f32_e32 v46, v46, v55
	v_mul_f32_e32 v47, v47, v55
	v_cvt_pk_bf16_f32 v96, v16, v20
	v_cvt_pk_bf16_f32 v97, v24, v28
	v_cvt_pk_bf16_f32 v98, v32, v36
	v_cvt_pk_bf16_f32 v99, v40, v44
	v_cvt_pk_bf16_f32 v100, v17, v21
	v_cvt_pk_bf16_f32 v101, v25, v29
	v_cvt_pk_bf16_f32 v102, v33, v37
	v_cvt_pk_bf16_f32 v103, v41, v45
	v_cvt_pk_bf16_f32 v104, v18, v22
	v_cvt_pk_bf16_f32 v105, v26, v30
	v_cvt_pk_bf16_f32 v106, v34, v38
	v_cvt_pk_bf16_f32 v107, v42, v46
	v_cvt_pk_bf16_f32 v108, v19, v23
	v_cvt_pk_bf16_f32 v109, v27, v31
	v_cvt_pk_bf16_f32 v110, v35, v39
	v_cvt_pk_bf16_f32 v111, v43, v47
	v_mad_u32_u24 v12, v7, s46, v10
	s_mov_b32 s4, s44
	s_mov_b32 s5, s45
	global_store_dwordx4 v12, v[96:99], s[4:5]
	s_add_u32 s4, s4, s46
	s_addc_u32 s5, s5, 0
	global_store_dwordx4 v12, v[100:103], s[4:5]
	s_add_u32 s4, s4, s46
	s_addc_u32 s5, s5, 0
	global_store_dwordx4 v12, v[104:107], s[4:5]
	s_add_u32 s4, s4, s46
	s_addc_u32 s5, s5, 0
	global_store_dwordx4 v12, v[108:111], s[4:5]
	s_mov_b32 s39, 0
	s_cmp_eq_u32 s53, 0
	s_cbranch_scc1 .Lconv_return
	s_mov_b32 s34, s52
.Lconv_loopB:
	s_add_u32 s52, s34, s36
	s_cmp_lt_u32 s52, s35
	s_cselect_b32 s53, 1, 0
	s_cbranch_scc0 .Lconv_B_nonext
	v_readlane_b32 s42, v253, 63
	v_readlane_b32 s43, v254, 0
	s_cmpk_lt_u32 s52, 0x260
	s_cbranch_scc1 .Lconv_iA_m0
	s_cmpk_lt_u32 s52, 0x360
	s_cbranch_scc1 .Lconv_iA_m1
	s_cmpk_lt_u32 s52, 0x760
	s_cbranch_scc1 .Lconv_iA_m2
	s_sub_u32 s0, s52, 0x760
	s_and_b32 s1, s0, 15
	s_lshr_b32 s0, s0, 4
	v_readlane_b32 s40, v253, 23
	v_readlane_b32 s41, v253, 24
	s_mov_b32 s8, s37
	s_mov_b32 s9, 0
	s_lshl_b64 s[4:5], s[8:9], 26
	s_add_u32 s40, s40, s4
	s_addc_u32 s41, s41, s5
	s_lshl_b64 s[4:5], s[8:9], 25
	s_add_u32 s42, s42, s4
	s_addc_u32 s43, s43, s5
	s_add_u32 s42, s42, 0xec00000
	s_addc_u32 s43, s43, 0
	v_readlane_b32 s28, v252, 62
	v_readlane_b32 s29, v252, 63
	s_movk_i32 s30, 0x2000
	s_movk_i32 s46, 0x4000
	s_mov_b32 s47, 0
	s_branch .Lconv_iA_dec

; __device__ __forceinline__ void transpose_big(const Lt& lt, const float* src, bf16_t* dst, const float* scale, int K, int N, int tlo, int thi, int phase, int c, int nc, float* tile) {
;     ...
;         if (tnx < thi) { const int k1 = (tnx / tn) * 128, n1 = (tnx % tn) * 128;
; #pragma unroll
;             for (int h = 0; h < 8; ++h) pre[h] = __builtin_nontemporal_load((const f32x4*)(src + (size_t)(k1 + kr + 16 * h) * N + n1 + nc4)); }
.Lconv_iA_dec:
	s_lshl_b32 s4, s30, 7
	s_mul_i32 s4, s4, s0
	s_lshl_b32 s5, s1, 9
	s_add_u32 s4, s4, s5
	s_add_u32 s40, s40, s4
	s_addc_u32 s41, s41, 0
	s_lshl_b32 s4, s46, 7
	s_mul_i32 s4, s4, s1
	s_lshl_b32 s5, s0, 8
	s_add_u32 s4, s4, s5
	s_add_u32 s44, s42, s4
	s_addc_u32 s45, s43, 0
	s_lshl_b32 s4, s0, 9
	s_mul_i32 s4, s4, s47
	s_add_u32 s28, s28, s4
	s_addc_u32 s29, s29, 0
	v_mad_u32_u24 v11, v6, s30, v9
	global_load_dwordx4 v[16:19], v11, s[40:41] nt
	s_add_u32 s40, s40, s30
	s_addc_u32 s41, s41, 0
	global_load_dwordx4 v[20:23], v11, s[40:41] nt
	s_add_u32 s40, s40, s30
	s_addc_u32 s41, s41, 0
	global_load_dwordx4 v[24:27], v11, s[40:41] nt
	s_add_u32 s40, s40, s30
	s_addc_u32 s41, s41, 0
	global_load_dwordx4 v[28:31], v11, s[40:41] nt
	s_add_u32 s40, s40, s30
	s_addc_u32 s41, s41, 0
	global_load_dwordx4 v[32:35], v11, s[40:41] nt
	s_add_u32 s40, s40, s30
	s_addc_u32 s41, s41, 0
	global_load_dwordx4 v[36:39], v11, s[40:41] nt
	s_add_u32 s40, s40, s30
	s_addc_u32 s41, s41, 0
	global_load_dwordx4 v[40:43], v11, s[40:41] nt
	s_add_u32 s40, s40, s30
	s_addc_u32 s41, s41, 0
	global_load_dwordx4 v[44:47], v11, s[40:41] nt
	global_load_dwordx4 v[48:51], v8, s[28:29]
	global_load_dwordx4 v[52:55], v8, s[28:29] offset:16
	s_cmp_eq_u32 s39, 1
	s_cbranch_scc1 .Lconv_B_w10
	s_waitcnt vmcnt(14)
	s_branch .Lconv_B_go

; __device__ __forceinline__ unsigned cvt_pk_bf16(float lo, float hi) { const f32x2 v = {lo, hi}; return __builtin_bit_cast(unsigned, __builtin_convertvector(v, bf16x2_t)); }
; __device__ __forceinline__ void transpose_big(const Lt& lt, const float* src, bf16_t* dst, const float* scale, int K, int N, int tlo, int thi, int phase, int c, int nc, float* tile) {
;     ...
;         bf16_t* dp = dst + (size_t)(n0 + on) * K + k0 + okc;
; #pragma unroll
;         for (int q = 0; q < 4; ++q) {
;             float v[8];
; #pragma unroll
;             for (int i = 0; i < 8; ++i) v[i] = tile[(okc + q * 8 + i) * 129 + on];
;             if (scale) {
;                 const f32x4 s0 = *(const f32x4*)(scale + k0 + okc + q * 8), s1 = *(const f32x4*)(scale + k0 + okc + q * 8 + 4);
; #pragma unroll
;                 for (int i = 0; i < 4; ++i) { v[i] *= s0[i]; v[4 + i] *= s1[i]; }
;             }
;             u32x4 w; w.x = cvt_pk_bf16(v[0], v[1]); w.y = cvt_pk_bf16(v[2], v[3]); w.z = cvt_pk_bf16(v[4], v[5]); w.w = cvt_pk_bf16(v[6], v[7]);
;             *(u32x4*)(dp + q * 8) = w;
;         }
.Lconv_B_go:
	s_cmp_eq_u32 s51, 1
	s_cbranch_scc1 .Lconv_cB_hs
	v_mov_b32_e32 v88, 1.0
	v_mov_b32_e32 v89, 1.0
	v_mov_b32_e32 v90, 1.0
	v_mov_b32_e32 v91, 1.0
	v_mov_b32_e32 v92, 1.0
	v_mov_b32_e32 v93, 1.0
	v_mov_b32_e32 v94, 1.0
	v_mov_b32_e32 v95, 1.0
.Lconv_cB_hs:
	v_mul_f32_e32 v56, v56, v88
	v_mul_f32_e32 v57, v57, v88
	v_mul_f32_e32 v58, v58, v88
	v_mul_f32_e32 v59, v59, v88
	v_mul_f32_e32 v60, v60, v89
	v_mul_f32_e32 v61, v61, v89
	v_mul_f32_e32 v62, v62, v89
	v_mul_f32_e32 v63, v63, v89
	v_mul_f32_e32 v64, v64, v90
	v_mul_f32_e32 v65, v65, v90
	v_mul_f32_e32 v66, v66, v90
	v_mul_f32_e32 v67, v67, v90
	v_mul_f32_e32 v68, v68, v91
	v_mul_f32_e32 v69, v69, v91
	v_mul_f32_e32 v70, v70, v91
	v_mul_f32_e32 v71, v71, v91
	v_mul_f32_e32 v72, v72, v92
	v_mul_f32_e32 v73, v73, v92
	v_mul_f32_e32 v74, v74, v92
	v_mul_f32_e32 v75, v75, v92
	v_mul_f32_e32 v76, v76, v93
	v_mul_f32_e32 v77, v77, v93
	v_mul_f32_e32 v78, v78, v93
	v_mul_f32_e32 v79, v79, v93
	v_mul_f32_e32 v80, v80, v94
	v_mul_f32_e32 v81, v81, v94
	v_mul_f32_e32 v82, v82, v94
	v_mul_f32_e32 v83, v83, v94
	v_mul_f32_e32 v84, v84, v95
	v_mul_f32_e32 v85, v85, v95
	v_mul_f32_e32 v86, v86, v95
	v_mul_f32_e32 v87, v87, v95
	v_cvt_pk_bf16_f32 v96, v56, v60
	v_cvt_pk_bf16_f32 v97, v64, v68
	v_cvt_pk_bf16_f32 v98, v72, v76
	v_cvt_pk_bf16_f32 v99, v80, v84
	v_cvt_pk_bf16_f32 v100, v57, v61
	v_cvt_pk_bf16_f32 v101, v65, v69
	v_cvt_pk_bf16_f32 v102, v73, v77
	v_cvt_pk_bf16_f32 v103, v81, v85
	v_cvt_pk_bf16_f32 v104, v58, v62
	v_cvt_pk_bf16_f32 v105, v66, v70
	v_cvt_pk_bf16_f32 v106, v74, v78
	v_cvt_pk_bf16_f32 v107, v82, v86
	v_cvt_pk_bf16_f32 v108, v59, v63
	v_cvt_pk_bf16_f32 v109, v67, v71
	v_cvt_pk_bf16_f32 v110, v75, v79
	v_cvt_pk_bf16_f32 v111, v83, v87
	v_mad_u32_u24 v12, v7, s50, v10
	s_mov_b32 s4, s48
	s_mov_b32 s5, s49
	global_store_dwordx4 v12, v[96:99], s[4:5]
	s_add_u32 s4, s4, s50
	s_addc_u32 s5, s5, 0
	global_store_dwordx4 v12, v[100:103], s[4:5]
	s_add_u32 s4, s4, s50
	s_addc_u32 s5, s5, 0
	global_store_dwordx4 v12, v[104:107], s[4:5]
	s_add_u32 s4, s4, s50
	s_addc_u32 s5, s5, 0
	global_store_dwordx4 v12, v[108:111], s[4:5]
	s_mov_b32 s39, 0
	s_cmp_eq_u32 s53, 0
	s_cbranch_scc1 .Lconv_return
	s_mov_b32 s34, s52
	s_branch .Lconv_loopA
.Lconv_return:
	s_cmp_eq_u32 s38, 0
	s_cbranch_scc1 .Lconv_ret0
	s_cmp_eq_u32 s38, 1
	s_cbranch_scc1 .LBB0_464
	s_branch .LBB0_259

; template <bool COOP>
; __global__ void __launch_bounds__(NTHREADS, 2) mega(Params p0) {
;     ...
;                 if (G == 256 && lt.bid >= 96 && !(ph0 & 1)) { __syncthreads(); convert_layer(p, lt, l, 864, CONV_TILES, lt.bid - 96, 160, (float*)lds); } }
.LBB0_434:
	s_cmpk_lt_i32 s86, 0x60
	v_readlane_b32 s4, v253, 21
	s_cselect_b64 s[0:1], -1, 0
	v_readlane_b32 s5, v253, 22
	s_or_b64 s[0:1], s[4:5], s[0:1]
	s_and_b64 vcc, exec, s[0:1]
	s_cbranch_vccnz .LBB0_464
	v_readlane_b32 s37, v254, 1
	s_add_i32 s34, s86, 0x300
	s_movk_i32 s35, 0xb60
	s_movk_i32 s36, 0xa0
	s_mov_b32 s38, 1
	s_branch .Lconv_entry

; __device__ __forceinline__ void phase_prep(const Params& p, const Lt& lt, unsigned char* lds) {
;     ...
;     if (gridDim.x == 256) convert_layer(p, lt, 0, 0, 864, lt.bid, gridDim.x, tile);
.LBB0_471:
	v_readlane_b32 s0, v251, 9
	v_readlane_b32 s1, v251, 10
	s_and_b64 vcc, exec, s[0:1]
	s_cbranch_vccnz .Lconv_ret0
	s_mov_b32 s37, 0
	s_mov_b32 s34, s86
	s_movk_i32 s35, 0x360
	s_movk_i32 s36, 0x100
	s_mov_b32 s38, 0
	s_branch .Lconv_entry
.Lconv_ret0:
	s_add_u32 s4, s62, 0x6c00000
	s_addc_u32 s5, s63, 0
	s_waitcnt lgkmcnt(0)
	v_ashrrev_i32_e32 v2, 2, v245
	s_add_u32 s6, s62, 0x4c00000
	v_ashrrev_i32_e32 v57, 5, v245
	v_and_b32_e32 v0, 0xffffffe0, v2
	s_movk_i32 s0, 0x204
	v_or_b32_e32 v2, 31, v2
	s_addc_u32 s7, s63, 0
	v_lshlrev_b32_e32 v56, 2, v245
	v_mul_lo_u32 v62, v57, s0
	v_mul_lo_u32 v63, v0, s0
	v_mul_lo_u32 v64, v2, s0
	v_readlane_b32 s0, v251, 9
	s_add_u32 s8, s62, 0xec00000
	v_and_b32_e32 v58, 0x7f, v245
	v_and_b32_e32 v59, 0x7c, v56
	v_readlane_b32 s1, v251, 10
	s_addc_u32 s9, s63, 0
	v_lshl_add_u32 v60, v59, 2, 0
	v_ashrrev_i32_e32 v1, 31, v0
	v_lshl_add_u32 v61, v58, 2, 0
	s_andn2_b64 vcc, exec, s[0:1]
	s_mov_b64 s[0:1], 0
	s_cbranch_vccnz .LBB0_503
	s_mov_b32 s10, 0
	s_branch .LBB0_474

; __device__ __forceinline__ void transpose_job(const Lt& lt, const float* src, bf16_t* dst, const float* scale, int K, int N, int& rot, float* tile  ) {
;     const int tid = lt.tid, G = gridDim.x;
;     const int tk = K / 64, tn = N / 64, ntile = tk * tn;
;     const int first = (int)((lt.bid + G - (rot % G)) % G);
;     for (int t = first; t < ntile; t += G) {
;         const int k0 = (t / tn) * 64, n0 = (t % tn) * 64;
;         { const int kr = tid >> 4, nc = (tid & 15) * 4;
; #pragma unroll
;           for (int h = 0; h < 2; ++h) { const f32x4 v = *(const f32x4*)(src + (size_t)(k0 + kr + h * 32) * N + n0 + nc);
;               float* tp = tile + (kr + h * 32) * 65 + nc; tp[0] = v[0]; tp[1] = v[1]; tp[2] = v[2]; tp[3] = v[3]; } }
;         __syncthreads();
;         { const int n = tid >> 3, kc = (tid & 7) * 8; float v[8];
; #pragma unroll
;           for (int i = 0; i < 8; ++i) v[i] = tile[(kc + i) * 65 + n];
.LBB0_503:
.LBB0_530:
	v_lshlrev_b32_e32 v0, 2, v56
	v_readlane_b32 s36, v252, 60
	v_and_b32_e32 v2, 0xf0, v0
	v_readlane_b32 s37, v252, 61
	v_readlane_b32 s38, v252, 62
	v_readlane_b32 s39, v252, 63
	v_readlane_b32 s40, v253, 0
	v_readlane_b32 s41, v253, 1
	v_readlane_b32 s42, v253, 2
	v_readlane_b32 s43, v253, 3
	v_readlane_b32 s44, v253, 4
	v_readlane_b32 s45, v253, 5
	v_readlane_b32 s46, v253, 6
	v_readlane_b32 s47, v253, 7
	v_readlane_b32 s48, v253, 8
	v_readlane_b32 s49, v253, 9
	v_readlane_b32 s50, v253, 10
	v_readlane_b32 s51, v253, 11
	v_lshl_add_u64 v[0:1], s[46:47], 0, v[2:3]
	s_waitcnt vmcnt(0) lgkmcnt(0)
	v_lshlrev_b32_e32 v4, 3, v245
	v_lshl_add_u64 v[6:7], s[50:51], 0, v[2:3]
	v_readlane_b32 s36, v253, 27
	s_add_u32 s8, s62, 0x16c00000
	v_ashrrev_i32_e32 v5, 4, v245
	v_ashrrev_i32_e32 v13, 3, v245
	v_and_b32_e32 v4, 56, v4
	s_movk_i32 s0, 0x104
	v_readlane_b32 s37, v253, 28
	s_mov_b32 s10, 0
	s_addc_u32 s9, s63, 0
	s_add_i32 s28, s86, s89
	v_add_u32_e32 v12, 0, v2
	v_lshl_add_u32 v14, v13, 2, 0
	v_mul_u32_u24_e32 v15, 0x104, v4
	v_mul_lo_u32 v16, v5, s0
	v_lshl_add_u64 v[8:9], s[36:37], 0, v[2:3]
	s_mov_b32 s29, s10
	v_readlane_b32 s38, v253, 29
	v_readlane_b32 s39, v253, 30
	v_readlane_b32 s40, v253, 31
	v_readlane_b32 s41, v253, 32
	v_readlane_b32 s42, v253, 33
	v_readlane_b32 s43, v253, 34
	v_readlane_b32 s44, v253, 35
	v_readlane_b32 s45, v253, 36
	v_readlane_b32 s46, v253, 37
	v_readlane_b32 s47, v253, 38
	v_readlane_b32 s48, v253, 39
	v_readlane_b32 s49, v253, 40
	v_readlane_b32 s50, v253, 41
	v_readlane_b32 s51, v253, 42
	s_branch .LBB0_532
